# out-proj residual GEMM epilogue: f32 residual rows prefetched two rows ahead into dead fragment registers, waits never cover stores
# baseline (speedup 1.0000x reference)
; DEVI unsigned pk2(float lo, float hi) { unsigned r; asm("v_cvt_pk_bf16_f32 %0, %1, %2" : "=v"(r) : "v"(lo), "v"(hi)); return r; }
; template <int M> DEVI float shx(float v) { return __int_as_float(__builtin_amdgcn_ds_swizzle(__float_as_int(v), (M << 10) | 0x1f)); }
; DEVI float shx32(float v, int lane) { return __int_as_float(__builtin_amdgcn_ds_bpermute((lane ^ 32) << 2, __float_as_int(v))); }
;   DEVI void operator()(const f32x4 (&acc)[2][2][4][2], const pg8::Unit& u, int wr, int wc, int fr, int fq) const {
; #pragma unroll
;     for (int ai = 0; ai < 2; ++ai)
; #pragma unroll
;       for (int m = 0; m < 4; ++m) {
;         const int row = u.pm * 256 + ai * 128 + wr * 64 + m * 16 + fr;
;         const bool use_snap = snap && (row & 2047) == 0;
;         float ss = 0.f;
; #pragma unroll
;         for (int bj = 0; bj < 2; ++bj) {
;           const int col = u.pn * 256 + bj * 128 + wc * 32 + fq * 8;
;           float* p = xf + (size_t)row * DM + col;
;           f32x4 x0 = *(const f32x4*)p, x1 = *(const f32x4*)(p + 4);
;           x0 += acc[ai][bj][m][0]; x1 += acc[ai][bj][m][1];
;           if (use_snap) { const float* sp = snap + (size_t)(row >> 11) * 1024 + col; x0 = *(const f32x4*)sp; x1 = *(const f32x4*)(sp + 4); }
;           *(f32x4*)p = x0; *(f32x4*)(p + 4) = x1;
;           u32x4 w; w.x = pk2(x0[0], x0[1]); w.y = pk2(x0[2], x0[3]); w.z = pk2(x1[0], x1[1]); w.w = pk2(x1[2], x1[3]);
;           *(u32x4*)(xb + (size_t)row * DM + col) = w;
;           ss += (x0[0] * x0[0] + x0[1] * x0[1] + x0[2] * x0[2] + x0[3] * x0[3]) + (x1[0] * x1[0] + x1[1] * x1[1] + x1[2] * x1[2] + x1[3] * x1[3]);
;         }
;         ss += shx<16>(ss); ss += shx32(ss, fq * 16 + fr);
;         if (fq == 0) ssout[(size_t)row * 16 + u.pn * 4 + wc] = ss;
;       }
.LBB0_1725:
	s_lshl_b32 s15, s40, 8
	s_add_i32 s15, s15, s36
	v_or_b32_e32 v148, s15, v131
	v_ashrrev_i32_e32 v149, 31, v148
	v_readlane_b32 s24, v252, 40
	v_lshl_or_b32 v146, s39, 8, v151
	v_lshlrev_b64 v[132:133], 12, v[148:149]
	v_readlane_b32 s25, v252, 41
	v_ashrrev_i32_e32 v147, 31, v146
	s_lshl_b32 s22, s39, 2
	v_lshl_add_u64 v[132:133], s[24:25], 0, v[132:133]
	v_lshl_add_u64 v[160:161], v[146:147], 2, v[132:133]
	v_mov_b32_e32 v162, 0x10000
	v_mov_b32_e32 v163, 0
	v_mov_b32_e32 v196, v160
	v_mov_b32_e32 v197, v161
	v_lshl_add_u64 v[198:199], v[196:197], 0, v[162:163]
	v_lshl_add_u64 v[200:201], v[198:199], 0, v[162:163]
	v_lshl_add_u64 v[202:203], v[200:201], 0, v[162:163]
	v_lshl_add_u64 v[204:205], v[162:163], 3, v[196:197]
	v_lshl_add_u64 v[206:207], v[204:205], 0, v[162:163]
	v_lshl_add_u64 v[208:209], v[206:207], 0, v[162:163]
	v_lshl_add_u64 v[210:211], v[208:209], 0, v[162:163]
	global_load_dwordx4 v[164:167], v[196:197], off offset:16
	global_load_dwordx4 v[168:171], v[196:197], off
	global_load_dwordx4 v[172:175], v[196:197], off offset:528
	global_load_dwordx4 v[176:179], v[196:197], off offset:512
	global_load_dwordx4 v[180:183], v[198:199], off offset:16
	global_load_dwordx4 v[184:187], v[198:199], off
	global_load_dwordx4 v[188:191], v[198:199], off offset:528
	global_load_dwordx4 v[192:195], v[198:199], off offset:512
	s_waitcnt vmcnt(4)
	v_mov_b32_e32 v132, v164
	v_mov_b32_e32 v133, v165
	v_mov_b32_e32 v134, v166
	v_mov_b32_e32 v135, v167
	v_mov_b32_e32 v156, v168
	v_mov_b32_e32 v157, v169
	v_mov_b32_e32 v158, v170
	v_mov_b32_e32 v159, v171
	v_readlane_b32 s24, v254, 6
	v_readlane_b32 s25, v254, 7
	s_ashr_i32 s23, s22, 31
	v_readlane_b32 s26, v252, 42
	v_readlane_b32 s27, v252, 43
	v_pk_add_f32 v[122:123], v[122:123], v[132:133]
	v_pk_add_f32 v[128:129], v[128:129], v[158:159]
	v_pk_add_f32 v[126:127], v[126:127], v[156:157]
	v_pk_add_f32 v[124:125], v[124:125], v[134:135]
	global_store_dwordx4 v[160:161], v[126:129], off
	global_store_dwordx4 v[160:161], v[122:125], off offset:16
	v_cvt_pk_bf16_f32 v132, v126, v127
	v_cvt_pk_bf16_f32 v134, v122, v123
	v_lshlrev_b64 v[156:157], 11, v[148:149]
	v_mul_f32_e32 v127, v127, v127
	v_mul_f32_e32 v123, v123, v123
	v_lshl_add_u64 v[156:157], s[24:25], 0, v[156:157]
	v_fmac_f32_e32 v127, v126, v126
	v_fmac_f32_e32 v123, v122, v122
	v_lshl_add_u64 v[156:157], v[146:147], 1, v[156:157]
	v_fmac_f32_e32 v127, v128, v128
	v_fmac_f32_e32 v123, v124, v124
	v_cvt_pk_bf16_f32 v133, v128, v129
	v_cvt_pk_bf16_f32 v135, v124, v125
	global_store_dwordx4 v[156:157], v[132:135], off
	v_fmac_f32_e32 v127, v129, v129
	v_fmac_f32_e32 v123, v125, v125
	v_add_f32_e32 v132, v127, v123
	s_nop 1
	v_mov_b32_e32 v122, v172
	v_mov_b32_e32 v123, v173
	v_mov_b32_e32 v124, v174
	v_mov_b32_e32 v125, v175
	v_mov_b32_e32 v126, v176
	v_mov_b32_e32 v127, v177
	v_mov_b32_e32 v128, v178
	v_mov_b32_e32 v129, v179
	global_load_dwordx4 v[164:167], v[200:201], off offset:16
	global_load_dwordx4 v[168:171], v[200:201], off
	global_load_dwordx4 v[172:175], v[200:201], off offset:528
	global_load_dwordx4 v[176:179], v[200:201], off offset:512
	v_pk_add_f32 v[114:115], v[114:115], v[122:123]
	v_pk_add_f32 v[120:121], v[120:121], v[128:129]
	v_pk_add_f32 v[118:119], v[118:119], v[126:127]
	v_pk_add_f32 v[116:117], v[116:117], v[124:125]
	global_store_dwordx4 v[160:161], v[118:121], off offset:512
	global_store_dwordx4 v[160:161], v[114:117], off offset:528
	v_cvt_pk_bf16_f32 v122, v118, v119
	v_cvt_pk_bf16_f32 v124, v114, v115
	v_cvt_pk_bf16_f32 v123, v120, v121
	v_cvt_pk_bf16_f32 v125, v116, v117
	s_nop 0
	v_mul_f32_e32 v119, v119, v119
	v_mul_f32_e32 v115, v115, v115
	v_fmac_f32_e32 v119, v118, v118
	v_fmac_f32_e32 v115, v114, v114
	v_fmac_f32_e32 v119, v120, v120
	v_fmac_f32_e32 v115, v116, v116
	v_fmac_f32_e32 v119, v121, v121
	v_fmac_f32_e32 v115, v117, v117
	v_add_f32_e32 v114, v119, v115
	v_add_f32_e32 v114, v132, v114
	ds_swizzle_b32 v115, v114 offset:swizzle(SWAP,16)
	global_store_dwordx4 v[156:157], v[122:125], off offset:256
	s_waitcnt lgkmcnt(0)
	v_add_f32_e32 v114, v114, v115
	ds_bpermute_b32 v115, v152, v114
	s_and_saveexec_b64 s[24:25], s[4:5]
	s_cbranch_execz .LBB0_1727
	v_lshlrev_b64 v[116:117], 6, v[148:149]
	v_lshl_add_u64 v[116:117], s[54:55], 0, v[116:117]
	v_lshl_add_u64 v[116:117], s[22:23], 2, v[116:117]
	s_lshl_b32 s26, s35, 2
	s_mov_b32 s27, s93
	v_lshl_add_u64 v[116:117], v[116:117], 0, s[26:27]
	s_waitcnt lgkmcnt(0)
	v_add_f32_e32 v114, v114, v115
	global_store_dword v[116:117], v114, off
; DEVI unsigned pk2(float lo, float hi) { unsigned r; asm("v_cvt_pk_bf16_f32 %0, %1, %2" : "=v"(r) : "v"(lo), "v"(hi)); return r; }
; template <int M> DEVI float shx(float v) { return __int_as_float(__builtin_amdgcn_ds_swizzle(__float_as_int(v), (M << 10) | 0x1f)); }
; DEVI float shx32(float v, int lane) { return __int_as_float(__builtin_amdgcn_ds_bpermute((lane ^ 32) << 2, __float_as_int(v))); }
;   DEVI void operator()(const f32x4 (&acc)[2][2][4][2], const pg8::Unit& u, int wr, int wc, int fr, int fq) const {
;     ...
;       for (int m = 0; m < 4; ++m) {
;         const int row = u.pm * 256 + ai * 128 + wr * 64 + m * 16 + fr;
;         const bool use_snap = snap && (row & 2047) == 0;
;         float ss = 0.f;
; #pragma unroll
;         for (int bj = 0; bj < 2; ++bj) {
;           const int col = u.pn * 256 + bj * 128 + wc * 32 + fq * 8;
;           float* p = xf + (size_t)row * DM + col;
;           f32x4 x0 = *(const f32x4*)p, x1 = *(const f32x4*)(p + 4);
;           x0 += acc[ai][bj][m][0]; x1 += acc[ai][bj][m][1];
;           if (use_snap) { const float* sp = snap + (size_t)(row >> 11) * 1024 + col; x0 = *(const f32x4*)sp; x1 = *(const f32x4*)(sp + 4); }
;           *(f32x4*)p = x0; *(f32x4*)(p + 4) = x1;
;           u32x4 w; w.x = pk2(x0[0], x0[1]); w.y = pk2(x0[2], x0[3]); w.z = pk2(x1[0], x1[1]); w.w = pk2(x1[2], x1[3]);
;           *(u32x4*)(xb + (size_t)row * DM + col) = w;
;           ss += (x0[0] * x0[0] + x0[1] * x0[1] + x0[2] * x0[2] + x0[3] * x0[3]) + (x1[0] * x1[0] + x1[1] * x1[1] + x1[2] * x1[2] + x1[3] * x1[3]);
;         }
;         ss += shx<16>(ss); ss += shx32(ss, fq * 16 + fr);
;         if (fq == 0) ssout[(size_t)row * 16 + u.pn * 4 + wc] = ss;
;       }
.LBB0_1727:
	s_or_b64 exec, exec, s[24:25]
	v_or_b32_e32 v114, 16, v148
	s_waitcnt lgkmcnt(0)
	v_ashrrev_i32_e32 v115, 31, v114
	v_readlane_b32 s24, v252, 40
	v_lshlrev_b64 v[116:117], 12, v[114:115]
	v_readlane_b32 s25, v252, 41
	v_lshlrev_b64 v[126:127], 11, v[114:115]
	v_readlane_b32 s26, v252, 42
	v_lshl_add_u64 v[116:117], s[24:25], 0, v[116:117]
	v_lshl_add_u64 v[124:125], v[146:147], 2, v[116:117]
	s_waitcnt vmcnt(11)
	v_mov_b32_e32 v116, v180
	v_mov_b32_e32 v117, v181
	v_mov_b32_e32 v118, v182
	v_mov_b32_e32 v119, v183
	v_mov_b32_e32 v120, v184
	v_mov_b32_e32 v121, v185
	v_mov_b32_e32 v122, v186
	v_mov_b32_e32 v123, v187
	v_readlane_b32 s24, v254, 6
	v_readlane_b32 s25, v254, 7
	v_readlane_b32 s27, v252, 43
	v_pk_add_f32 v[108:109], v[108:109], v[118:119]
	v_lshl_add_u64 v[126:127], s[24:25], 0, v[126:127]
	v_lshl_add_u64 v[126:127], v[146:147], 1, v[126:127]
	v_pk_add_f32 v[112:113], v[112:113], v[122:123]
	v_pk_add_f32 v[110:111], v[110:111], v[120:121]
	v_pk_add_f32 v[106:107], v[106:107], v[116:117]
	global_store_dwordx4 v[124:125], v[110:113], off
	global_store_dwordx4 v[124:125], v[106:109], off offset:16
	v_cvt_pk_bf16_f32 v116, v110, v111
	v_cvt_pk_bf16_f32 v117, v112, v113
	v_cvt_pk_bf16_f32 v118, v106, v107
	v_cvt_pk_bf16_f32 v119, v108, v109
	global_store_dwordx4 v[126:127], v[116:119], off
	s_nop 1
	v_mov_b32_e32 v116, v188
	v_mov_b32_e32 v117, v189
	v_mov_b32_e32 v118, v190
	v_mov_b32_e32 v119, v191
	v_mov_b32_e32 v120, v192
	v_mov_b32_e32 v121, v193
	v_mov_b32_e32 v122, v194
	v_mov_b32_e32 v123, v195
	global_load_dwordx4 v[180:183], v[202:203], off offset:16
	global_load_dwordx4 v[184:187], v[202:203], off
	global_load_dwordx4 v[188:191], v[202:203], off offset:528
	global_load_dwordx4 v[192:195], v[202:203], off offset:512
	v_mul_f32_e32 v111, v111, v111
	v_mul_f32_e32 v107, v107, v107
	v_fmac_f32_e32 v111, v110, v110
	v_fmac_f32_e32 v107, v106, v106
	v_fmac_f32_e32 v111, v112, v112
	v_fmac_f32_e32 v107, v108, v108
	v_fmac_f32_e32 v111, v113, v113
	v_fmac_f32_e32 v107, v109, v109
	v_add_f32_e32 v110, v107, v111
	v_pk_add_f32 v[106:107], v[98:99], v[116:117]
	v_pk_add_f32 v[98:99], v[102:103], v[120:121]
	v_mul_f32_e32 v103, v107, v107
	v_mul_f32_e32 v102, v99, v99
	v_pk_add_f32 v[108:109], v[100:101], v[118:119]
	v_pk_add_f32 v[100:101], v[104:105], v[122:123]
	v_fmac_f32_e32 v102, v98, v98
	v_fmac_f32_e32 v103, v106, v106
	v_fmac_f32_e32 v102, v100, v100
	v_fmac_f32_e32 v103, v108, v108
	v_fmac_f32_e32 v102, v101, v101
	v_fmac_f32_e32 v103, v109, v109
	v_add_f32_e32 v102, v103, v102
	v_add_f32_e32 v103, v110, v102
	ds_swizzle_b32 v104, v103 offset:swizzle(SWAP,16)
	global_store_dwordx4 v[124:125], v[98:101], off offset:512
	global_store_dwordx4 v[124:125], v[106:109], off offset:528
	v_cvt_pk_bf16_f32 v102, v98, v99
	v_cvt_pk_bf16_f32 v105, v108, v109
	s_waitcnt lgkmcnt(0)
	v_add_f32_e32 v98, v103, v104
	ds_bpermute_b32 v99, v152, v98
	v_cvt_pk_bf16_f32 v103, v100, v101
	v_cvt_pk_bf16_f32 v104, v106, v107
	global_store_dwordx4 v[126:127], v[102:105], off offset:256
	s_and_saveexec_b64 s[24:25], s[4:5]
	s_cbranch_execz .LBB0_1729
	v_lshlrev_b64 v[100:101], 6, v[114:115]
	v_lshl_add_u64 v[100:101], s[54:55], 0, v[100:101]
	v_lshl_add_u64 v[100:101], s[22:23], 2, v[100:101]
	s_lshl_b32 s26, s35, 2
	s_mov_b32 s27, s93
	v_lshl_add_u64 v[100:101], v[100:101], 0, s[26:27]
	s_waitcnt lgkmcnt(0)
	v_add_f32_e32 v98, v98, v99
	global_store_dword v[100:101], v98, off
.LBB0_1729:
	s_or_b64 exec, exec, s[24:25]
	v_or_b32_e32 v98, 32, v148
	s_waitcnt lgkmcnt(0)
	v_ashrrev_i32_e32 v99, 31, v98
	v_readlane_b32 s24, v252, 40
	v_lshlrev_b64 v[100:101], 12, v[98:99]
	v_readlane_b32 s25, v252, 41
	v_lshlrev_b64 v[110:111], 11, v[98:99]
	v_readlane_b32 s26, v252, 42
	v_lshl_add_u64 v[100:101], s[24:25], 0, v[100:101]
	v_lshl_add_u64 v[108:109], v[146:147], 2, v[100:101]
	s_waitcnt vmcnt(15)
	v_mov_b32_e32 v100, v164
	v_mov_b32_e32 v101, v165
	v_mov_b32_e32 v102, v166
	v_mov_b32_e32 v103, v167
	v_mov_b32_e32 v104, v168
	v_mov_b32_e32 v105, v169
	v_mov_b32_e32 v106, v170
	v_mov_b32_e32 v107, v171
	v_readlane_b32 s24, v254, 6
	v_readlane_b32 s25, v254, 7
	v_readlane_b32 s27, v252, 43
	v_pk_add_f32 v[92:93], v[92:93], v[102:103]
	v_lshl_add_u64 v[110:111], s[24:25], 0, v[110:111]
	v_lshl_add_u64 v[110:111], v[146:147], 1, v[110:111]
	v_pk_add_f32 v[96:97], v[96:97], v[106:107]
	v_pk_add_f32 v[94:95], v[94:95], v[104:105]
	v_pk_add_f32 v[90:91], v[90:91], v[100:101]
	global_store_dwordx4 v[108:109], v[94:97], off
	global_store_dwordx4 v[108:109], v[90:93], off offset:16
	v_cvt_pk_bf16_f32 v100, v94, v95
	v_cvt_pk_bf16_f32 v101, v96, v97
	v_cvt_pk_bf16_f32 v102, v90, v91
	v_cvt_pk_bf16_f32 v103, v92, v93
	global_store_dwordx4 v[110:111], v[100:103], off
	s_nop 1
	v_mov_b32_e32 v100, v172
	v_mov_b32_e32 v101, v173
	v_mov_b32_e32 v102, v174
	v_mov_b32_e32 v103, v175
	v_mov_b32_e32 v104, v176
	v_mov_b32_e32 v105, v177
	v_mov_b32_e32 v106, v178
	v_mov_b32_e32 v107, v179
	global_load_dwordx4 v[164:167], v[204:205], off offset:16
	global_load_dwordx4 v[168:171], v[204:205], off
	global_load_dwordx4 v[172:175], v[204:205], off offset:528
	global_load_dwordx4 v[176:179], v[204:205], off offset:512
	v_mul_f32_e32 v95, v95, v95
	v_mul_f32_e32 v91, v91, v91
	v_fmac_f32_e32 v95, v94, v94
	v_fmac_f32_e32 v91, v90, v90
	v_fmac_f32_e32 v95, v96, v96
	v_fmac_f32_e32 v91, v92, v92
	v_fmac_f32_e32 v95, v97, v97
	v_fmac_f32_e32 v91, v93, v93
	v_add_f32_e32 v94, v91, v95
	v_pk_add_f32 v[90:91], v[82:83], v[100:101]
	v_pk_add_f32 v[82:83], v[86:87], v[104:105]
	v_mul_f32_e32 v87, v91, v91
	v_mul_f32_e32 v86, v83, v83
	v_pk_add_f32 v[92:93], v[84:85], v[102:103]
	v_pk_add_f32 v[84:85], v[88:89], v[106:107]
	v_fmac_f32_e32 v86, v82, v82
	v_fmac_f32_e32 v87, v90, v90
	v_fmac_f32_e32 v86, v84, v84
	v_fmac_f32_e32 v87, v92, v92
	v_fmac_f32_e32 v86, v85, v85
	v_fmac_f32_e32 v87, v93, v93
	v_add_f32_e32 v86, v87, v86
	v_add_f32_e32 v87, v94, v86
	ds_swizzle_b32 v88, v87 offset:swizzle(SWAP,16)
	global_store_dwordx4 v[108:109], v[82:85], off offset:512
	global_store_dwordx4 v[108:109], v[90:93], off offset:528
	v_cvt_pk_bf16_f32 v86, v82, v83
	v_cvt_pk_bf16_f32 v89, v92, v93
	s_waitcnt lgkmcnt(0)
	v_add_f32_e32 v82, v87, v88
	ds_bpermute_b32 v83, v152, v82
	v_cvt_pk_bf16_f32 v87, v84, v85
	v_cvt_pk_bf16_f32 v88, v90, v91
	global_store_dwordx4 v[110:111], v[86:89], off offset:256
	s_and_saveexec_b64 s[24:25], s[4:5]
	s_cbranch_execz .LBB0_1731
	v_lshlrev_b64 v[84:85], 6, v[98:99]
	v_lshl_add_u64 v[84:85], s[54:55], 0, v[84:85]
	v_lshl_add_u64 v[84:85], s[22:23], 2, v[84:85]
	s_lshl_b32 s26, s35, 2
	s_mov_b32 s27, s93
	v_lshl_add_u64 v[84:85], v[84:85], 0, s[26:27]
	s_waitcnt lgkmcnt(0)
	v_add_f32_e32 v82, v82, v83
	global_store_dword v[84:85], v82, off
; DEVI unsigned pk2(float lo, float hi) { unsigned r; asm("v_cvt_pk_bf16_f32 %0, %1, %2" : "=v"(r) : "v"(lo), "v"(hi)); return r; }
; template <int M> DEVI float shx(float v) { return __int_as_float(__builtin_amdgcn_ds_swizzle(__float_as_int(v), (M << 10) | 0x1f)); }
; DEVI float shx32(float v, int lane) { return __int_as_float(__builtin_amdgcn_ds_bpermute((lane ^ 32) << 2, __float_as_int(v))); }
;   DEVI void operator()(const f32x4 (&acc)[2][2][4][2], const pg8::Unit& u, int wr, int wc, int fr, int fq) const {
;     ...
;       for (int m = 0; m < 4; ++m) {
;         const int row = u.pm * 256 + ai * 128 + wr * 64 + m * 16 + fr;
;         const bool use_snap = snap && (row & 2047) == 0;
;         float ss = 0.f;
; #pragma unroll
;         for (int bj = 0; bj < 2; ++bj) {
;           const int col = u.pn * 256 + bj * 128 + wc * 32 + fq * 8;
;           float* p = xf + (size_t)row * DM + col;
;           f32x4 x0 = *(const f32x4*)p, x1 = *(const f32x4*)(p + 4);
;           x0 += acc[ai][bj][m][0]; x1 += acc[ai][bj][m][1];
;           if (use_snap) { const float* sp = snap + (size_t)(row >> 11) * 1024 + col; x0 = *(const f32x4*)sp; x1 = *(const f32x4*)(sp + 4); }
;           *(f32x4*)p = x0; *(f32x4*)(p + 4) = x1;
;           u32x4 w; w.x = pk2(x0[0], x0[1]); w.y = pk2(x0[2], x0[3]); w.z = pk2(x1[0], x1[1]); w.w = pk2(x1[2], x1[3]);
;           *(u32x4*)(xb + (size_t)row * DM + col) = w;
;           ss += (x0[0] * x0[0] + x0[1] * x0[1] + x0[2] * x0[2] + x0[3] * x0[3]) + (x1[0] * x1[0] + x1[1] * x1[1] + x1[2] * x1[2] + x1[3] * x1[3]);
;         }
;         ss += shx<16>(ss); ss += shx32(ss, fq * 16 + fr);
;         if (fq == 0) ssout[(size_t)row * 16 + u.pn * 4 + wc] = ss;
;       }
.LBB0_1731:
	s_or_b64 exec, exec, s[24:25]
	v_or_b32_e32 v82, 48, v148
	s_waitcnt lgkmcnt(0)
	v_ashrrev_i32_e32 v83, 31, v82
	v_readlane_b32 s24, v252, 40
	v_lshlrev_b64 v[84:85], 12, v[82:83]
	v_readlane_b32 s25, v252, 41
	v_lshlrev_b64 v[94:95], 11, v[82:83]
	v_readlane_b32 s26, v252, 42
	v_lshl_add_u64 v[84:85], s[24:25], 0, v[84:85]
	v_lshl_add_u64 v[92:93], v[146:147], 2, v[84:85]
	s_waitcnt vmcnt(15)
	v_mov_b32_e32 v84, v180
	v_mov_b32_e32 v85, v181
	v_mov_b32_e32 v86, v182
	v_mov_b32_e32 v87, v183
	v_mov_b32_e32 v88, v184
	v_mov_b32_e32 v89, v185
	v_mov_b32_e32 v90, v186
	v_mov_b32_e32 v91, v187
	v_readlane_b32 s24, v254, 6
	v_readlane_b32 s25, v254, 7
	v_readlane_b32 s27, v252, 43
	v_pk_add_f32 v[76:77], v[76:77], v[86:87]
	v_lshl_add_u64 v[94:95], s[24:25], 0, v[94:95]
	v_lshl_add_u64 v[94:95], v[146:147], 1, v[94:95]
	v_pk_add_f32 v[80:81], v[80:81], v[90:91]
	v_pk_add_f32 v[78:79], v[78:79], v[88:89]
	v_pk_add_f32 v[74:75], v[74:75], v[84:85]
	global_store_dwordx4 v[92:93], v[78:81], off
	global_store_dwordx4 v[92:93], v[74:77], off offset:16
	v_cvt_pk_bf16_f32 v84, v78, v79
	v_cvt_pk_bf16_f32 v85, v80, v81
	v_cvt_pk_bf16_f32 v86, v74, v75
	v_cvt_pk_bf16_f32 v87, v76, v77
	global_store_dwordx4 v[94:95], v[84:87], off
	s_nop 1
	v_mov_b32_e32 v84, v188
	v_mov_b32_e32 v85, v189
	v_mov_b32_e32 v86, v190
	v_mov_b32_e32 v87, v191
	v_mov_b32_e32 v88, v192
	v_mov_b32_e32 v89, v193
	v_mov_b32_e32 v90, v194
	v_mov_b32_e32 v91, v195
	global_load_dwordx4 v[180:183], v[206:207], off offset:16
	global_load_dwordx4 v[184:187], v[206:207], off
	global_load_dwordx4 v[188:191], v[206:207], off offset:528
	global_load_dwordx4 v[192:195], v[206:207], off offset:512
	v_mul_f32_e32 v79, v79, v79
	v_mul_f32_e32 v75, v75, v75
	v_fmac_f32_e32 v79, v78, v78
	v_fmac_f32_e32 v75, v74, v74
	v_fmac_f32_e32 v79, v80, v80
	v_fmac_f32_e32 v75, v76, v76
	v_fmac_f32_e32 v79, v81, v81
	v_fmac_f32_e32 v75, v77, v77
	v_add_f32_e32 v78, v75, v79
	v_pk_add_f32 v[74:75], v[66:67], v[84:85]
	v_pk_add_f32 v[66:67], v[70:71], v[88:89]
	v_mul_f32_e32 v71, v75, v75
	v_mul_f32_e32 v70, v67, v67
	v_pk_add_f32 v[76:77], v[68:69], v[86:87]
	v_pk_add_f32 v[68:69], v[72:73], v[90:91]
	v_fmac_f32_e32 v70, v66, v66
	v_fmac_f32_e32 v71, v74, v74
	v_fmac_f32_e32 v70, v68, v68
	v_fmac_f32_e32 v71, v76, v76
	v_fmac_f32_e32 v70, v69, v69
	v_fmac_f32_e32 v71, v77, v77
	v_add_f32_e32 v70, v71, v70
	v_add_f32_e32 v71, v78, v70
	ds_swizzle_b32 v72, v71 offset:swizzle(SWAP,16)
	global_store_dwordx4 v[92:93], v[66:69], off offset:512
	global_store_dwordx4 v[92:93], v[74:77], off offset:528
	v_cvt_pk_bf16_f32 v70, v66, v67
	v_cvt_pk_bf16_f32 v73, v76, v77
	s_waitcnt lgkmcnt(0)
	v_add_f32_e32 v66, v71, v72
	ds_bpermute_b32 v67, v152, v66
	v_cvt_pk_bf16_f32 v71, v68, v69
	v_cvt_pk_bf16_f32 v72, v74, v75
	global_store_dwordx4 v[94:95], v[70:73], off offset:256
	s_and_saveexec_b64 s[24:25], s[4:5]
	s_cbranch_execz .LBB0_1733
	v_lshlrev_b64 v[68:69], 6, v[82:83]
	v_lshl_add_u64 v[68:69], s[54:55], 0, v[68:69]
	v_lshl_add_u64 v[68:69], s[22:23], 2, v[68:69]
	s_lshl_b32 s26, s35, 2
	s_mov_b32 s27, s93
	v_lshl_add_u64 v[68:69], v[68:69], 0, s[26:27]
	s_waitcnt lgkmcnt(0)
	v_add_f32_e32 v66, v66, v67
	global_store_dword v[68:69], v66, off
.LBB0_1733:
	s_or_b64 exec, exec, s[24:25]
	v_add_u32_e32 v66, s15, v153
	s_waitcnt lgkmcnt(0)
	v_ashrrev_i32_e32 v67, 31, v66
	v_readlane_b32 s24, v252, 40
	v_lshlrev_b64 v[68:69], 12, v[66:67]
	v_readlane_b32 s25, v252, 41
	v_readlane_b32 s26, v252, 42
	v_readlane_b32 s27, v252, 43
	v_lshl_add_u64 v[68:69], s[24:25], 0, v[68:69]
	v_lshl_add_u64 v[76:77], v[146:147], 2, v[68:69]
	s_waitcnt vmcnt(15)
	v_mov_b32_e32 v68, v164
	v_mov_b32_e32 v69, v165
	v_mov_b32_e32 v70, v166
	v_mov_b32_e32 v71, v167
	v_mov_b32_e32 v72, v168
	v_mov_b32_e32 v73, v169
	v_mov_b32_e32 v74, v170
	v_mov_b32_e32 v75, v171
	v_readlane_b32 s24, v254, 6
	v_readlane_b32 s25, v254, 7
	v_pk_add_f32 v[58:59], v[58:59], v[68:69]
	v_pk_add_f32 v[64:65], v[64:65], v[74:75]
	v_pk_add_f32 v[62:63], v[62:63], v[72:73]
	v_pk_add_f32 v[60:61], v[60:61], v[70:71]
	global_store_dwordx4 v[76:77], v[62:65], off
	global_store_dwordx4 v[76:77], v[58:61], off offset:16
	v_cvt_pk_bf16_f32 v68, v62, v63
	v_cvt_pk_bf16_f32 v70, v58, v59
	v_lshlrev_b64 v[72:73], 11, v[66:67]
	v_mul_f32_e32 v63, v63, v63
	v_mul_f32_e32 v59, v59, v59
	v_lshl_add_u64 v[72:73], s[24:25], 0, v[72:73]
	v_fmac_f32_e32 v63, v62, v62
	v_fmac_f32_e32 v59, v58, v58
	v_lshl_add_u64 v[72:73], v[146:147], 1, v[72:73]
	v_fmac_f32_e32 v63, v64, v64
	v_fmac_f32_e32 v59, v60, v60
	v_cvt_pk_bf16_f32 v69, v64, v65
	v_cvt_pk_bf16_f32 v71, v60, v61
	global_store_dwordx4 v[72:73], v[68:71], off
	v_fmac_f32_e32 v63, v65, v65
	v_fmac_f32_e32 v59, v61, v61
	v_add_f32_e32 v68, v63, v59
	s_nop 1
	v_mov_b32_e32 v58, v172
	v_mov_b32_e32 v59, v173
	v_mov_b32_e32 v60, v174
	v_mov_b32_e32 v61, v175
	v_mov_b32_e32 v62, v176
	v_mov_b32_e32 v63, v177
	v_mov_b32_e32 v64, v178
	v_mov_b32_e32 v65, v179
	global_load_dwordx4 v[164:167], v[208:209], off offset:16
	global_load_dwordx4 v[168:171], v[208:209], off
	global_load_dwordx4 v[172:175], v[208:209], off offset:528
	global_load_dwordx4 v[176:179], v[208:209], off offset:512
	v_pk_add_f32 v[50:51], v[50:51], v[58:59]
	v_pk_add_f32 v[56:57], v[56:57], v[64:65]
	v_pk_add_f32 v[54:55], v[54:55], v[62:63]
	v_pk_add_f32 v[52:53], v[52:53], v[60:61]
	global_store_dwordx4 v[76:77], v[54:57], off offset:512
	global_store_dwordx4 v[76:77], v[50:53], off offset:528
	v_cvt_pk_bf16_f32 v58, v54, v55
	v_cvt_pk_bf16_f32 v60, v50, v51
	v_cvt_pk_bf16_f32 v59, v56, v57
	v_cvt_pk_bf16_f32 v61, v52, v53
	s_nop 0
	v_mul_f32_e32 v55, v55, v55
	v_mul_f32_e32 v51, v51, v51
	v_fmac_f32_e32 v55, v54, v54
	v_fmac_f32_e32 v51, v50, v50
	v_fmac_f32_e32 v55, v56, v56
	v_fmac_f32_e32 v51, v52, v52
	v_fmac_f32_e32 v55, v57, v57
	v_fmac_f32_e32 v51, v53, v53
	v_add_f32_e32 v50, v55, v51
	v_add_f32_e32 v50, v68, v50
	ds_swizzle_b32 v51, v50 offset:swizzle(SWAP,16)
	global_store_dwordx4 v[72:73], v[58:61], off offset:256
	s_waitcnt lgkmcnt(0)
	v_add_f32_e32 v50, v50, v51
	ds_bpermute_b32 v51, v152, v50
	s_and_saveexec_b64 s[24:25], s[4:5]
	s_cbranch_execz .LBB0_1735
	v_lshlrev_b64 v[52:53], 6, v[66:67]
	v_lshl_add_u64 v[52:53], s[54:55], 0, v[52:53]
	v_lshl_add_u64 v[52:53], s[22:23], 2, v[52:53]
	s_lshl_b32 s26, s35, 2
	s_mov_b32 s27, s93
	v_lshl_add_u64 v[52:53], v[52:53], 0, s[26:27]
	s_waitcnt lgkmcnt(0)
	v_add_f32_e32 v50, v50, v51
	global_store_dword v[52:53], v50, off
; DEVI unsigned pk2(float lo, float hi) { unsigned r; asm("v_cvt_pk_bf16_f32 %0, %1, %2" : "=v"(r) : "v"(lo), "v"(hi)); return r; }
; template <int M> DEVI float shx(float v) { return __int_as_float(__builtin_amdgcn_ds_swizzle(__float_as_int(v), (M << 10) | 0x1f)); }
; DEVI float shx32(float v, int lane) { return __int_as_float(__builtin_amdgcn_ds_bpermute((lane ^ 32) << 2, __float_as_int(v))); }
;   DEVI void operator()(const f32x4 (&acc)[2][2][4][2], const pg8::Unit& u, int wr, int wc, int fr, int fq) const {
;     ...
;       for (int m = 0; m < 4; ++m) {
;         const int row = u.pm * 256 + ai * 128 + wr * 64 + m * 16 + fr;
;         const bool use_snap = snap && (row & 2047) == 0;
;         float ss = 0.f;
; #pragma unroll
;         for (int bj = 0; bj < 2; ++bj) {
;           const int col = u.pn * 256 + bj * 128 + wc * 32 + fq * 8;
;           float* p = xf + (size_t)row * DM + col;
;           f32x4 x0 = *(const f32x4*)p, x1 = *(const f32x4*)(p + 4);
;           x0 += acc[ai][bj][m][0]; x1 += acc[ai][bj][m][1];
;           if (use_snap) { const float* sp = snap + (size_t)(row >> 11) * 1024 + col; x0 = *(const f32x4*)sp; x1 = *(const f32x4*)(sp + 4); }
;           *(f32x4*)p = x0; *(f32x4*)(p + 4) = x1;
;           u32x4 w; w.x = pk2(x0[0], x0[1]); w.y = pk2(x0[2], x0[3]); w.z = pk2(x1[0], x1[1]); w.w = pk2(x1[2], x1[3]);
;           *(u32x4*)(xb + (size_t)row * DM + col) = w;
;           ss += (x0[0] * x0[0] + x0[1] * x0[1] + x0[2] * x0[2] + x0[3] * x0[3]) + (x1[0] * x1[0] + x1[1] * x1[1] + x1[2] * x1[2] + x1[3] * x1[3]);
;         }
;         ss += shx<16>(ss); ss += shx32(ss, fq * 16 + fr);
;         if (fq == 0) ssout[(size_t)row * 16 + u.pn * 4 + wc] = ss;
;       }
.LBB0_1735:
	s_or_b64 exec, exec, s[24:25]
	v_or_b32_e32 v50, 16, v66
	s_waitcnt lgkmcnt(0)
	v_ashrrev_i32_e32 v51, 31, v50
	v_readlane_b32 s24, v252, 40
	v_lshlrev_b64 v[52:53], 12, v[50:51]
	v_readlane_b32 s25, v252, 41
	v_readlane_b32 s26, v252, 42
	v_readlane_b32 s27, v252, 43
	v_lshl_add_u64 v[52:53], s[24:25], 0, v[52:53]
	v_lshl_add_u64 v[60:61], v[146:147], 2, v[52:53]
	s_waitcnt vmcnt(15)
	v_mov_b32_e32 v52, v180
	v_mov_b32_e32 v53, v181
	v_mov_b32_e32 v54, v182
	v_mov_b32_e32 v55, v183
	v_mov_b32_e32 v56, v184
	v_mov_b32_e32 v57, v185
	v_mov_b32_e32 v58, v186
	v_mov_b32_e32 v59, v187
	v_readlane_b32 s24, v254, 6
	v_readlane_b32 s25, v254, 7
	v_pk_add_f32 v[42:43], v[42:43], v[52:53]
	v_pk_add_f32 v[48:49], v[48:49], v[58:59]
	v_pk_add_f32 v[46:47], v[46:47], v[56:57]
	v_pk_add_f32 v[44:45], v[44:45], v[54:55]
	global_store_dwordx4 v[60:61], v[46:49], off
	global_store_dwordx4 v[60:61], v[42:45], off offset:16
	v_cvt_pk_bf16_f32 v52, v46, v47
	v_cvt_pk_bf16_f32 v54, v42, v43
	v_lshlrev_b64 v[56:57], 11, v[50:51]
	v_mul_f32_e32 v47, v47, v47
	v_mul_f32_e32 v43, v43, v43
	v_lshl_add_u64 v[56:57], s[24:25], 0, v[56:57]
	v_fmac_f32_e32 v47, v46, v46
	v_fmac_f32_e32 v43, v42, v42
	v_lshl_add_u64 v[56:57], v[146:147], 1, v[56:57]
	v_fmac_f32_e32 v47, v48, v48
	v_fmac_f32_e32 v43, v44, v44
	v_cvt_pk_bf16_f32 v53, v48, v49
	v_cvt_pk_bf16_f32 v55, v44, v45
	global_store_dwordx4 v[56:57], v[52:55], off
	v_fmac_f32_e32 v47, v49, v49
	v_fmac_f32_e32 v43, v45, v45
	v_add_f32_e32 v52, v47, v43
	s_nop 1
	v_mov_b32_e32 v42, v188
	v_mov_b32_e32 v43, v189
	v_mov_b32_e32 v44, v190
	v_mov_b32_e32 v45, v191
	v_mov_b32_e32 v46, v192
	v_mov_b32_e32 v47, v193
	v_mov_b32_e32 v48, v194
	v_mov_b32_e32 v49, v195
	global_load_dwordx4 v[180:183], v[210:211], off offset:16
	global_load_dwordx4 v[184:187], v[210:211], off
	global_load_dwordx4 v[188:191], v[210:211], off offset:528
	global_load_dwordx4 v[192:195], v[210:211], off offset:512
	v_pk_add_f32 v[34:35], v[34:35], v[42:43]
	v_pk_add_f32 v[40:41], v[40:41], v[48:49]
	v_pk_add_f32 v[38:39], v[38:39], v[46:47]
	v_pk_add_f32 v[36:37], v[36:37], v[44:45]
	global_store_dwordx4 v[60:61], v[38:41], off offset:512
	global_store_dwordx4 v[60:61], v[34:37], off offset:528
	v_cvt_pk_bf16_f32 v42, v38, v39
	v_cvt_pk_bf16_f32 v44, v34, v35
	v_cvt_pk_bf16_f32 v43, v40, v41
	v_cvt_pk_bf16_f32 v45, v36, v37
	s_nop 0
	v_mul_f32_e32 v39, v39, v39
	v_mul_f32_e32 v35, v35, v35
	v_fmac_f32_e32 v39, v38, v38
	v_fmac_f32_e32 v35, v34, v34
	v_fmac_f32_e32 v39, v40, v40
	v_fmac_f32_e32 v35, v36, v36
	v_fmac_f32_e32 v39, v41, v41
	v_fmac_f32_e32 v35, v37, v37
	v_add_f32_e32 v34, v39, v35
	v_add_f32_e32 v34, v52, v34
	ds_swizzle_b32 v35, v34 offset:swizzle(SWAP,16)
	global_store_dwordx4 v[56:57], v[42:45], off offset:256
	s_waitcnt lgkmcnt(0)
	v_add_f32_e32 v34, v34, v35
	ds_bpermute_b32 v35, v152, v34
	s_and_saveexec_b64 s[24:25], s[4:5]
	s_cbranch_execz .LBB0_1737
	v_lshlrev_b64 v[36:37], 6, v[50:51]
	v_lshl_add_u64 v[36:37], s[54:55], 0, v[36:37]
	v_lshl_add_u64 v[36:37], s[22:23], 2, v[36:37]
	s_lshl_b32 s26, s35, 2
	s_mov_b32 s27, s93
	v_lshl_add_u64 v[36:37], v[36:37], 0, s[26:27]
	s_waitcnt lgkmcnt(0)
	v_add_f32_e32 v34, v34, v35
	global_store_dword v[36:37], v34, off
; DEVI unsigned pk2(float lo, float hi) { unsigned r; asm("v_cvt_pk_bf16_f32 %0, %1, %2" : "=v"(r) : "v"(lo), "v"(hi)); return r; }
; template <int M> DEVI float shx(float v) { return __int_as_float(__builtin_amdgcn_ds_swizzle(__float_as_int(v), (M << 10) | 0x1f)); }
; DEVI float shx32(float v, int lane) { return __int_as_float(__builtin_amdgcn_ds_bpermute((lane ^ 32) << 2, __float_as_int(v))); }
;   DEVI void operator()(const f32x4 (&acc)[2][2][4][2], const pg8::Unit& u, int wr, int wc, int fr, int fq) const {
;     ...
;       for (int m = 0; m < 4; ++m) {
;         const int row = u.pm * 256 + ai * 128 + wr * 64 + m * 16 + fr;
;         const bool use_snap = snap && (row & 2047) == 0;
;         float ss = 0.f;
; #pragma unroll
;         for (int bj = 0; bj < 2; ++bj) {
;           const int col = u.pn * 256 + bj * 128 + wc * 32 + fq * 8;
;           float* p = xf + (size_t)row * DM + col;
;           f32x4 x0 = *(const f32x4*)p, x1 = *(const f32x4*)(p + 4);
;           x0 += acc[ai][bj][m][0]; x1 += acc[ai][bj][m][1];
;           if (use_snap) { const float* sp = snap + (size_t)(row >> 11) * 1024 + col; x0 = *(const f32x4*)sp; x1 = *(const f32x4*)(sp + 4); }
;           *(f32x4*)p = x0; *(f32x4*)(p + 4) = x1;
;           u32x4 w; w.x = pk2(x0[0], x0[1]); w.y = pk2(x0[2], x0[3]); w.z = pk2(x1[0], x1[1]); w.w = pk2(x1[2], x1[3]);
;           *(u32x4*)(xb + (size_t)row * DM + col) = w;
;           ss += (x0[0] * x0[0] + x0[1] * x0[1] + x0[2] * x0[2] + x0[3] * x0[3]) + (x1[0] * x1[0] + x1[1] * x1[1] + x1[2] * x1[2] + x1[3] * x1[3]);
;         }
;         ss += shx<16>(ss); ss += shx32(ss, fq * 16 + fr);
;         if (fq == 0) ssout[(size_t)row * 16 + u.pn * 4 + wc] = ss;
;       }
.LBB0_1737:
	s_or_b64 exec, exec, s[24:25]
	v_or_b32_e32 v34, 32, v66
	s_waitcnt lgkmcnt(0)
	v_ashrrev_i32_e32 v35, 31, v34
	v_readlane_b32 s24, v252, 40
	v_lshlrev_b64 v[36:37], 12, v[34:35]
	v_readlane_b32 s25, v252, 41
	v_readlane_b32 s26, v252, 42
	v_readlane_b32 s27, v252, 43
	v_lshl_add_u64 v[36:37], s[24:25], 0, v[36:37]
	v_lshl_add_u64 v[44:45], v[146:147], 2, v[36:37]
	s_waitcnt vmcnt(15)
	v_mov_b32_e32 v36, v164
	v_mov_b32_e32 v37, v165
	v_mov_b32_e32 v38, v166
	v_mov_b32_e32 v39, v167
	v_mov_b32_e32 v40, v168
	v_mov_b32_e32 v41, v169
	v_mov_b32_e32 v42, v170
	v_mov_b32_e32 v43, v171
	v_readlane_b32 s24, v254, 6
	v_readlane_b32 s25, v254, 7
	v_pk_add_f32 v[24:25], v[24:25], v[36:37]
	v_pk_add_f32 v[30:31], v[30:31], v[42:43]
	v_pk_add_f32 v[28:29], v[28:29], v[40:41]
	v_pk_add_f32 v[26:27], v[26:27], v[38:39]
	global_store_dwordx4 v[44:45], v[28:31], off
	global_store_dwordx4 v[44:45], v[24:27], off offset:16
	v_cvt_pk_bf16_f32 v36, v28, v29
	v_cvt_pk_bf16_f32 v38, v24, v25
	v_lshlrev_b64 v[40:41], 11, v[34:35]
	v_mul_f32_e32 v29, v29, v29
	v_mul_f32_e32 v25, v25, v25
	v_lshl_add_u64 v[40:41], s[24:25], 0, v[40:41]
	v_fmac_f32_e32 v29, v28, v28
	v_fmac_f32_e32 v25, v24, v24
	v_lshl_add_u64 v[40:41], v[146:147], 1, v[40:41]
	v_fmac_f32_e32 v29, v30, v30
	v_fmac_f32_e32 v25, v26, v26
	v_cvt_pk_bf16_f32 v37, v30, v31
	v_cvt_pk_bf16_f32 v39, v26, v27
	global_store_dwordx4 v[40:41], v[36:39], off
	v_fmac_f32_e32 v29, v31, v31
	v_fmac_f32_e32 v25, v27, v27
	v_add_f32_e32 v36, v29, v25
	s_nop 1
	v_mov_b32_e32 v24, v172
	v_mov_b32_e32 v25, v173
	v_mov_b32_e32 v26, v174
	v_mov_b32_e32 v27, v175
	v_mov_b32_e32 v28, v176
	v_mov_b32_e32 v29, v177
	v_mov_b32_e32 v30, v178
	v_mov_b32_e32 v31, v179
	v_pk_add_f32 v[16:17], v[16:17], v[24:25]
	v_pk_add_f32 v[22:23], v[22:23], v[30:31]
	v_pk_add_f32 v[20:21], v[20:21], v[28:29]
	v_pk_add_f32 v[18:19], v[18:19], v[26:27]
	global_store_dwordx4 v[44:45], v[20:23], off offset:512
	global_store_dwordx4 v[44:45], v[16:19], off offset:528
	v_cvt_pk_bf16_f32 v24, v20, v21
	v_cvt_pk_bf16_f32 v26, v16, v17
	v_cvt_pk_bf16_f32 v25, v22, v23
	v_cvt_pk_bf16_f32 v27, v18, v19
	s_nop 0
	v_mul_f32_e32 v21, v21, v21
	v_mul_f32_e32 v17, v17, v17
	v_fmac_f32_e32 v21, v20, v20
	v_fmac_f32_e32 v17, v16, v16
	v_fmac_f32_e32 v21, v22, v22
	v_fmac_f32_e32 v17, v18, v18
	v_fmac_f32_e32 v21, v23, v23
	v_fmac_f32_e32 v17, v19, v19
	v_add_f32_e32 v16, v21, v17
	v_add_f32_e32 v16, v36, v16
	ds_swizzle_b32 v17, v16 offset:swizzle(SWAP,16)
	global_store_dwordx4 v[40:41], v[24:27], off offset:256
	s_waitcnt lgkmcnt(0)
	v_add_f32_e32 v16, v16, v17
	ds_bpermute_b32 v17, v152, v16
	s_and_saveexec_b64 s[24:25], s[4:5]
	s_cbranch_execz .LBB0_1739
	v_lshlrev_b64 v[18:19], 6, v[34:35]
	v_lshl_add_u64 v[18:19], s[54:55], 0, v[18:19]
	v_lshl_add_u64 v[18:19], s[22:23], 2, v[18:19]
	s_lshl_b32 s26, s35, 2
	s_mov_b32 s27, s93
	v_lshl_add_u64 v[18:19], v[18:19], 0, s[26:27]
	s_waitcnt lgkmcnt(0)
	v_add_f32_e32 v16, v16, v17
	global_store_dword v[18:19], v16, off
.LBB0_1739:
	s_or_b64 exec, exec, s[24:25]
	v_or_b32_e32 v16, 48, v66
	s_waitcnt lgkmcnt(0)
	v_ashrrev_i32_e32 v17, 31, v16
	v_readlane_b32 s24, v252, 40
	v_lshlrev_b64 v[18:19], 12, v[16:17]
	v_readlane_b32 s25, v252, 41
	v_readlane_b32 s26, v252, 42
	v_readlane_b32 s27, v252, 43
	v_lshl_add_u64 v[18:19], s[24:25], 0, v[18:19]
	v_lshl_add_u64 v[26:27], v[146:147], 2, v[18:19]
	s_waitcnt vmcnt(11)
	v_mov_b32_e32 v18, v180
	v_mov_b32_e32 v19, v181
	v_mov_b32_e32 v20, v182
	v_mov_b32_e32 v21, v183
	v_mov_b32_e32 v22, v184
	v_mov_b32_e32 v23, v185
	v_mov_b32_e32 v24, v186
	v_mov_b32_e32 v25, v187
	v_readlane_b32 s24, v254, 6
	v_readlane_b32 s25, v254, 7
	v_pk_add_f32 v[8:9], v[8:9], v[18:19]
	v_pk_add_f32 v[14:15], v[14:15], v[24:25]
	v_pk_add_f32 v[12:13], v[12:13], v[22:23]
	v_pk_add_f32 v[10:11], v[10:11], v[20:21]
	global_store_dwordx4 v[26:27], v[12:15], off
	global_store_dwordx4 v[26:27], v[8:11], off offset:16
	v_cvt_pk_bf16_f32 v18, v12, v13
	v_cvt_pk_bf16_f32 v20, v8, v9
	v_lshlrev_b64 v[22:23], 11, v[16:17]
	v_mul_f32_e32 v13, v13, v13
	v_mul_f32_e32 v9, v9, v9
	v_lshl_add_u64 v[22:23], s[24:25], 0, v[22:23]
	v_fmac_f32_e32 v13, v12, v12
	v_fmac_f32_e32 v9, v8, v8
	v_lshl_add_u64 v[22:23], v[146:147], 1, v[22:23]
	v_fmac_f32_e32 v13, v14, v14
	v_fmac_f32_e32 v9, v10, v10
	v_cvt_pk_bf16_f32 v19, v14, v15
	v_cvt_pk_bf16_f32 v21, v10, v11
	global_store_dwordx4 v[22:23], v[18:21], off
	v_fmac_f32_e32 v13, v15, v15
	v_fmac_f32_e32 v9, v11, v11
	v_add_f32_e32 v18, v13, v9
	s_nop 1
	v_mov_b32_e32 v8, v188
	v_mov_b32_e32 v9, v189
	v_mov_b32_e32 v10, v190
	v_mov_b32_e32 v11, v191
	v_mov_b32_e32 v12, v192
	v_mov_b32_e32 v13, v193
	v_mov_b32_e32 v14, v194
	v_mov_b32_e32 v15, v195
	v_pk_add_f32 v[0:1], v[0:1], v[8:9]
	v_pk_add_f32 v[6:7], v[6:7], v[14:15]
	v_pk_add_f32 v[4:5], v[4:5], v[12:13]
	v_pk_add_f32 v[2:3], v[2:3], v[10:11]
	global_store_dwordx4 v[26:27], v[4:7], off offset:512
	global_store_dwordx4 v[26:27], v[0:3], off offset:528
	v_cvt_pk_bf16_f32 v8, v4, v5
	v_cvt_pk_bf16_f32 v10, v0, v1
	v_cvt_pk_bf16_f32 v9, v6, v7
	v_cvt_pk_bf16_f32 v11, v2, v3
	s_nop 0
	v_mul_f32_e32 v5, v5, v5
	v_mul_f32_e32 v1, v1, v1
	v_fmac_f32_e32 v5, v4, v4
	v_fmac_f32_e32 v1, v0, v0
	v_fmac_f32_e32 v5, v6, v6
	v_fmac_f32_e32 v1, v2, v2
	v_fmac_f32_e32 v5, v7, v7
	v_fmac_f32_e32 v1, v3, v3
	v_add_f32_e32 v0, v5, v1
	v_add_f32_e32 v0, v18, v0
	ds_swizzle_b32 v1, v0 offset:swizzle(SWAP,16)
	global_store_dwordx4 v[22:23], v[8:11], off offset:256
	s_waitcnt lgkmcnt(0)
	v_add_f32_e32 v0, v0, v1
	ds_bpermute_b32 v1, v152, v0
	s_and_saveexec_b64 s[24:25], s[4:5]
	s_cbranch_execz .LBB0_1741
	v_lshlrev_b64 v[2:3], 6, v[16:17]
	v_lshl_add_u64 v[2:3], s[54:55], 0, v[2:3]
	v_lshl_add_u64 v[2:3], s[22:23], 2, v[2:3]
	s_lshl_b32 s22, s35, 2
	s_mov_b32 s23, s93
	v_lshl_add_u64 v[2:3], v[2:3], 0, s[22:23]
	s_waitcnt lgkmcnt(0)
	v_add_f32_e32 v0, v0, v1
	global_store_dword v[2:3], v0, off
